# adds: in-proj and out GEMM K-loops: LDS read-address adds and DMA base setup hoisted in front of the loop (no VALU instruction left in the staging part)
# baseline (speedup 1.0000x reference)
; __device__ __forceinline__ int lane_id_hw() { int l; asm volatile("v_mbcnt_lo_u32_b32 %0, -1, 0\n\tv_mbcnt_hi_u32_b32 %0, -1, %0" : "=v"(l)); return l; }
; #define PG8_STAGE(bufoff, gbase, voff) do { unsigned _g = (gbase); asm volatile("" : "+s"(_g));   _Pragma("unroll") for (int _i = 0; _i < 2; ++_i) \
;         __builtin_amdgcn_global_load_lds((const unsigned*)(wsb + (size_t)(unsigned)(_g + (voff)[_i])), (LAS unsigned*)(lds + (bufoff) + ldsw + _i * 8192), 16, 0, 0); } while (0)
; #define PG8_SCHED __builtin_amdgcn_sched_barrier(0)
;     ...
;         for (int t = 0; t < nt; t += 2) {
;             if constexpr (Epi::HAS_MID) { if (t == Epi::MID0 || t == Epi::MID1) { const int l2 = lane_id_hw(); E.mid(acc, cur, t == Epi::MID0 ? 0 : 1, wr, wc, l2 & 15, l2 >> 4); } }
;             const bool last = (t == nt - 2);
;             const unsigned a1 = cA + (unsigned)(t + 1) * kstep;
;             const unsigned a2 = last ? nA : cA + (unsigned)(t + 2) * kstep, b2 = last ? nB : cB + (unsigned)(t + 2) * kstep;
;             const unsigned a3 = a2 + kstep, b3 = b2 + kstep;
;             if constexpr (SP2) {
;             PG8_LDB(B0, 0, 0); PG8_LDB(B1, 0, 1); PG8_SCHED; PG8_LDA(At, 0, 0); PG8_STAGE(PG8_SA(1, 1), a1 + hstep, voffA);
;     ...
;         for (int a = 0; a < 2; ++a)
; #pragma unroll
;             for (int b = 0; b < 2; ++b)
; #pragma unroll
;                 for (int m = 0; m < 4; ++m)
; #pragma unroll
;                     for (int n = 0; n < 2; ++n) acc[a][b][m][n] = (f32x4){0.f, 0.f, 0.f, 0.f};
;         cur = nxt; cA = nA; cB = nB; ++ui;
.LBB0_278:
	s_xor_b64 s[36:37], s[4:5], -1
	s_and_b64 s[4:5], s[4:5], exec
	v_mov_b32_e32 v2, 0
	s_cselect_b32 s4, s90, s11
	s_cselect_b32 s5, s91, s10
	s_add_i32 s8, s11, 0x100080
	s_add_i32 s9, s10, 0x100
	s_mov_b32 s10, -2
	v_mov_b32_e32 v3, v2
	v_mov_b32_e32 v4, v2
	v_mov_b32_e32 v5, v2
	v_mov_b32_e32 v6, v2
	v_mov_b32_e32 v7, v2
	v_mov_b32_e32 v8, v2
	v_mov_b32_e32 v9, v2
	v_mov_b32_e32 v18, v2
	v_mov_b32_e32 v19, v2
	v_mov_b32_e32 v20, v2
	v_mov_b32_e32 v21, v2
	v_mov_b32_e32 v22, v2
	v_mov_b32_e32 v23, v2
	v_mov_b32_e32 v24, v2
	v_mov_b32_e32 v25, v2
	v_mov_b32_e32 v34, v2
	v_mov_b32_e32 v35, v2
	v_mov_b32_e32 v36, v2
	v_mov_b32_e32 v37, v2
	v_mov_b32_e32 v38, v2
	v_mov_b32_e32 v39, v2
	v_mov_b32_e32 v40, v2
	v_mov_b32_e32 v41, v2
	v_mov_b32_e32 v50, v2
	v_mov_b32_e32 v51, v2
	v_mov_b32_e32 v52, v2
	v_mov_b32_e32 v53, v2
	v_mov_b32_e32 v54, v2
	v_mov_b32_e32 v55, v2
	v_mov_b32_e32 v56, v2
	v_mov_b32_e32 v57, v2
	v_mov_b32_e32 v10, v2
	v_mov_b32_e32 v11, v2
	v_mov_b32_e32 v12, v2
	v_mov_b32_e32 v13, v2
	v_mov_b32_e32 v14, v2
	v_mov_b32_e32 v15, v2
	v_mov_b32_e32 v16, v2
	v_mov_b32_e32 v17, v2
	v_mov_b32_e32 v26, v2
	v_mov_b32_e32 v27, v2
	v_mov_b32_e32 v28, v2
	v_mov_b32_e32 v29, v2
	v_mov_b32_e32 v30, v2
	v_mov_b32_e32 v31, v2
	v_mov_b32_e32 v32, v2
	v_mov_b32_e32 v33, v2
	v_mov_b32_e32 v42, v2
	v_mov_b32_e32 v43, v2
	v_mov_b32_e32 v44, v2
	v_mov_b32_e32 v45, v2
	v_mov_b32_e32 v46, v2
	v_mov_b32_e32 v47, v2
	v_mov_b32_e32 v48, v2
	v_mov_b32_e32 v49, v2
	v_mov_b32_e32 v58, v2
	v_mov_b32_e32 v59, v2
	v_mov_b32_e32 v60, v2
	v_mov_b32_e32 v61, v2
	v_mov_b32_e32 v62, v2
	v_mov_b32_e32 v63, v2
	v_mov_b32_e32 v64, v2
	v_mov_b32_e32 v65, v2
	v_mov_b32_e32 v66, v2
	v_mov_b32_e32 v67, v2
	v_mov_b32_e32 v68, v2
	v_mov_b32_e32 v69, v2
	v_mov_b32_e32 v70, v2
	v_mov_b32_e32 v71, v2
	v_mov_b32_e32 v72, v2
	v_mov_b32_e32 v73, v2
	v_mov_b32_e32 v82, v2
	v_mov_b32_e32 v83, v2
	v_mov_b32_e32 v84, v2
	v_mov_b32_e32 v85, v2
	v_mov_b32_e32 v86, v2
	v_mov_b32_e32 v87, v2
	v_mov_b32_e32 v88, v2
	v_mov_b32_e32 v89, v2
	v_mov_b32_e32 v98, v2
	v_mov_b32_e32 v99, v2
	v_mov_b32_e32 v100, v2
	v_mov_b32_e32 v101, v2
	v_mov_b32_e32 v102, v2
	v_mov_b32_e32 v103, v2
	v_mov_b32_e32 v104, v2
	v_mov_b32_e32 v105, v2
	v_mov_b32_e32 v114, v2
	v_mov_b32_e32 v115, v2
	v_mov_b32_e32 v116, v2
	v_mov_b32_e32 v117, v2
	v_mov_b32_e32 v118, v2
	v_mov_b32_e32 v119, v2
	v_mov_b32_e32 v120, v2
	v_mov_b32_e32 v121, v2
	v_mov_b32_e32 v74, v2
	v_mov_b32_e32 v75, v2
	v_mov_b32_e32 v76, v2
	v_mov_b32_e32 v77, v2
	v_mov_b32_e32 v78, v2
	v_mov_b32_e32 v79, v2
	v_mov_b32_e32 v80, v2
	v_mov_b32_e32 v81, v2
	v_mov_b32_e32 v90, v2
	v_mov_b32_e32 v91, v2
	v_mov_b32_e32 v92, v2
	v_mov_b32_e32 v93, v2
	v_mov_b32_e32 v94, v2
	v_mov_b32_e32 v95, v2
	v_mov_b32_e32 v96, v2
	v_mov_b32_e32 v97, v2
	v_mov_b32_e32 v106, v2
	v_mov_b32_e32 v107, v2
	v_mov_b32_e32 v108, v2
	v_mov_b32_e32 v109, v2
	v_mov_b32_e32 v110, v2
	v_mov_b32_e32 v111, v2
	v_mov_b32_e32 v112, v2
	v_mov_b32_e32 v113, v2
	v_mov_b32_e32 v122, v2
	v_mov_b32_e32 v123, v2
	v_mov_b32_e32 v124, v2
	v_mov_b32_e32 v125, v2
	v_mov_b32_e32 v126, v2
	v_mov_b32_e32 v127, v2
	v_mov_b32_e32 v128, v2
	v_mov_b32_e32 v129, v2
	v_readfirstlane_b32 s100, v130
	v_readfirstlane_b32 s101, v131
	s_nop 1
	s_sub_u32 s100, s100, 0x10000000
	s_subb_u32 s101, s101, 0
	v_add_u32_e32 v216, 0x10000, v152
	v_add_u32_e32 v217, 0x14000, v152
	v_add_u32_e32 v218, 0x18000, v152
	v_add_u32_e32 v219, 0x1c000, v152
.LBB0_279:
	s_add_i32 s11, s8, 0xfff00080
	s_cmp_eq_u32 s10, 60
	s_cselect_b32 s83, s4, s11
	s_cselect_b32 s82, s5, s9
	s_add_i32 s84, 0, 0x10000
	s_add_i32 s96, 0, 0x14000
	ds_read_b128 v[138:141], v216
	ds_read_b128 v[142:145], v216 offset:1024
	ds_read_b128 v[154:157], v216 offset:2048
	ds_read_b128 v[158:161], v216 offset:3072
	ds_read_b128 v[162:165], v217
	ds_read_b128 v[166:169], v217 offset:1024
	ds_read_b128 v[170:173], v217 offset:2048
	ds_read_b128 v[174:177], v217 offset:3072
	s_add_i32 s11, s83, 0x80
	s_mov_b32 s97, s8
	ds_read_b128 v[178:181], v153
	ds_read_b128 v[182:185], v153 offset:1024
	ds_read_b128 v[186:189], v153 offset:2048
	ds_read_b128 v[190:193], v153 offset:3072
	ds_read_b128 v[194:197], v153 offset:4096
	ds_read_b128 v[198:201], v153 offset:5120
	ds_read_b128 v[202:205], v153 offset:6144
	ds_read_b128 v[206:209], v153 offset:7168
	s_cmp_eq_i32 s10, -2
	s_cbranch_scc1 .Lin_g0_first

; #define PG8_STAGE(bufoff, gbase, voff) do { unsigned _g = (gbase); asm volatile("" : "+s"(_g));   _Pragma("unroll") for (int _i = 0; _i < 2; ++_i) \
;         __builtin_amdgcn_global_load_lds((const unsigned*)(wsb + (size_t)(unsigned)(_g + (voff)[_i])), (LAS unsigned*)(lds + (bufoff) + ldsw + _i * 8192), 16, 0, 0); } while (0)
; #define PG8_WAIT_V(n) asm volatile("s_waitcnt vmcnt(" #n ")" ::: "memory")
; #define PG8_WAIT_L(n) asm volatile("s_waitcnt lgkmcnt(" #n ")" ::: "memory")
; #define PG8_BAR __builtin_amdgcn_s_barrier()
; #define PG8_SCHED __builtin_amdgcn_sched_barrier(0)
;     ...
;             PG8_WAIT_V(8); PG8_WAIT_L(0); PG8_BAR; PG8_MMA(1, 0, At, B0); PG8_MMA(1, 1, At, B1); PG8_BAR; PG8_SCHED;
;             PG8_LDB(B0, 1, 0); PG8_LDB(B1, 1, 1); PG8_SCHED; PG8_LDA(At, 1, 0); PG8_STAGE(PG8_SA(0, 1), a2 + hstep, voffA);
.Lin_g1_join:
	s_waitcnt lgkmcnt(0)
	s_barrier
	s_setprio 1
	s_waitcnt lgkmcnt(0)
	v_mfma_f32_16x16x32_bf16 v[62:65], v[138:141], v[178:181], v[62:65]
	v_mfma_f32_16x16x32_bf16 v[58:61], v[154:157], v[178:181], v[58:61]
	v_mfma_f32_16x16x32_bf16 v[46:49], v[138:141], v[186:189], v[46:49]
	v_mfma_f32_16x16x32_bf16 v[42:45], v[154:157], v[186:189], v[42:45]
	v_mfma_f32_16x16x32_bf16 v[30:33], v[138:141], v[194:197], v[30:33]
	v_mfma_f32_16x16x32_bf16 v[26:29], v[154:157], v[194:197], v[26:29]
	v_mfma_f32_16x16x32_bf16 v[14:17], v[138:141], v[202:205], v[14:17]
	v_mfma_f32_16x16x32_bf16 v[10:13], v[154:157], v[202:205], v[10:13]
	v_mfma_f32_16x16x32_bf16 v[62:65], v[142:145], v[182:185], v[62:65]
	v_mfma_f32_16x16x32_bf16 v[58:61], v[158:161], v[182:185], v[58:61]
	v_mfma_f32_16x16x32_bf16 v[46:49], v[142:145], v[190:193], v[46:49]
	v_mfma_f32_16x16x32_bf16 v[42:45], v[158:161], v[190:193], v[42:45]
	v_mfma_f32_16x16x32_bf16 v[30:33], v[142:145], v[198:201], v[30:33]
	v_mfma_f32_16x16x32_bf16 v[26:29], v[158:161], v[198:201], v[26:29]
	v_mfma_f32_16x16x32_bf16 v[14:17], v[142:145], v[206:209], v[14:17]
	v_mfma_f32_16x16x32_bf16 v[10:13], v[158:161], v[206:209], v[10:13]
	s_setprio 0
	s_setprio 1
	v_mfma_f32_16x16x32_bf16 v[54:57], v[162:165], v[178:181], v[54:57]
	v_mfma_f32_16x16x32_bf16 v[50:53], v[170:173], v[178:181], v[50:53]
	v_mfma_f32_16x16x32_bf16 v[38:41], v[162:165], v[186:189], v[38:41]
	v_mfma_f32_16x16x32_bf16 v[34:37], v[170:173], v[186:189], v[34:37]
	v_mfma_f32_16x16x32_bf16 v[22:25], v[162:165], v[194:197], v[22:25]
	v_mfma_f32_16x16x32_bf16 v[18:21], v[170:173], v[194:197], v[18:21]
	v_mfma_f32_16x16x32_bf16 v[6:9], v[162:165], v[202:205], v[6:9]
	v_mfma_f32_16x16x32_bf16 v[2:5], v[170:173], v[202:205], v[2:5]
	v_mfma_f32_16x16x32_bf16 v[54:57], v[166:169], v[182:185], v[54:57]
	v_mfma_f32_16x16x32_bf16 v[50:53], v[174:177], v[182:185], v[50:53]
	v_mfma_f32_16x16x32_bf16 v[38:41], v[166:169], v[190:193], v[38:41]
	v_mfma_f32_16x16x32_bf16 v[34:37], v[174:177], v[190:193], v[34:37]
	v_mfma_f32_16x16x32_bf16 v[22:25], v[166:169], v[198:201], v[22:25]
	v_mfma_f32_16x16x32_bf16 v[18:21], v[174:177], v[198:201], v[18:21]
	v_mfma_f32_16x16x32_bf16 v[6:9], v[166:169], v[206:209], v[6:9]
	v_mfma_f32_16x16x32_bf16 v[2:5], v[174:177], v[206:209], v[2:5]
	s_setprio 0
	s_barrier
	s_add_i32 s84, 0, 0x18000
	s_add_i32 s96, 0, 0x1c000
	ds_read_b128 v[138:141], v218
	ds_read_b128 v[142:145], v218 offset:1024
	ds_read_b128 v[154:157], v218 offset:2048
	ds_read_b128 v[158:161], v218 offset:3072
	ds_read_b128 v[162:165], v219
	ds_read_b128 v[166:169], v219 offset:1024
	ds_read_b128 v[170:173], v219 offset:2048
	ds_read_b128 v[174:177], v219 offset:3072
	s_add_i32 s83, s83, 0x100000
	ds_read_b128 v[178:181], v153 offset:32768
	ds_read_b128 v[182:185], v153 offset:33792
	ds_read_b128 v[186:189], v153 offset:34816
	ds_read_b128 v[190:193], v153 offset:35840
	ds_read_b128 v[194:197], v153 offset:36864
	ds_read_b128 v[198:201], v153 offset:37888
	ds_read_b128 v[202:205], v153 offset:38912
	ds_read_b128 v[206:209], v153 offset:39936
	s_mov_b32 m0, s44
	s_add_i32 vcc_lo, s83, 0x10000000
	s_add_u32 vcc_lo, s100, vcc_lo
	s_addc_u32 vcc_hi, s101, 0
	global_load_lds_dwordx4 v148, vcc
	s_mov_b32 m0, s45
	s_nop 0
	global_load_lds_dwordx4 v150, vcc
	s_cmp_eq_i32 s10, -2
	s_cbranch_scc1 .Lin_g2_first

; __device__ __forceinline__ int lane_id_hw() { int l; asm volatile("v_mbcnt_lo_u32_b32 %0, -1, 0\n\tv_mbcnt_hi_u32_b32 %0, -1, %0" : "=v"(l)); return l; }
; #define PG8_STAGE(bufoff, gbase, voff) do { unsigned _g = (gbase); asm volatile("" : "+s"(_g));   _Pragma("unroll") for (int _i = 0; _i < 2; ++_i) \
;         __builtin_amdgcn_global_load_lds((const unsigned*)(wsb + (size_t)(unsigned)(_g + (voff)[_i])), (LAS unsigned*)(lds + (bufoff) + ldsw + _i * 8192), 16, 0, 0); } while (0)
; #define PG8_WAIT_V(n) asm volatile("s_waitcnt vmcnt(" #n ")" ::: "memory")
; #define PG8_WAIT_L(n) asm volatile("s_waitcnt lgkmcnt(" #n ")" ::: "memory")
; #define PG8_BAR __builtin_amdgcn_s_barrier()
; #define PG8_SCHED __builtin_amdgcn_sched_barrier(0)
;     ...
;         for (int t = 0; t < nt; t += 2) {
;             if constexpr (Epi::HAS_MID) { if (t == Epi::MID0 || t == Epi::MID1) { const int l2 = lane_id_hw(); E.mid(acc, cur, t == Epi::MID0 ? 0 : 1, wr, wc, l2 & 15, l2 >> 4); } }
;             const bool last = (t == nt - 2);
;             const unsigned a1 = cA + (unsigned)(t + 1) * kstep;
;             const unsigned a2 = last ? nA : cA + (unsigned)(t + 2) * kstep, b2 = last ? nB : cB + (unsigned)(t + 2) * kstep;
;             const unsigned a3 = a2 + kstep, b3 = b2 + kstep;
;             if constexpr (SP2) {
;             PG8_LDB(B0, 0, 0); PG8_LDB(B1, 0, 1); PG8_SCHED; PG8_LDA(At, 0, 0); PG8_STAGE(PG8_SA(1, 1), a1 + hstep, voffA);
;             PG8_WAIT_V(8); PG8_WAIT_L(0); PG8_BAR; PG8_MMA(0, 0, At, B0); PG8_MMA(0, 1, At, B1); PG8_BAR; PG8_SCHED;
;     ...
;         for (int a = 0; a < 2; ++a)
; #pragma unroll
;             for (int b = 0; b < 2; ++b)
; #pragma unroll
;                 for (int m = 0; m < 4; ++m)
; #pragma unroll
;                     for (int n = 0; n < 2; ++n) acc[a][b][m][n] = (f32x4){0.f, 0.f, 0.f, 0.f};
;         cur = nxt; cA = nA; cB = nB; ++ui;
.LBB0_861:
	v_mov_b32_e32 v2, 0
	s_add_i32 s10, s10, 0x100080
	s_addk_i32 s11, 0x100
	s_mov_b32 s18, -2
	v_mov_b32_e32 v3, v2
	v_mov_b32_e32 v4, v2
	v_mov_b32_e32 v5, v2
	v_mov_b32_e32 v6, v2
	v_mov_b32_e32 v7, v2
	v_mov_b32_e32 v8, v2
	v_mov_b32_e32 v9, v2
	v_mov_b32_e32 v18, v2
	v_mov_b32_e32 v19, v2
	v_mov_b32_e32 v20, v2
	v_mov_b32_e32 v21, v2
	v_mov_b32_e32 v22, v2
	v_mov_b32_e32 v23, v2
	v_mov_b32_e32 v24, v2
	v_mov_b32_e32 v25, v2
	v_mov_b32_e32 v34, v2
	v_mov_b32_e32 v35, v2
	v_mov_b32_e32 v36, v2
	v_mov_b32_e32 v37, v2
	v_mov_b32_e32 v38, v2
	v_mov_b32_e32 v39, v2
	v_mov_b32_e32 v40, v2
	v_mov_b32_e32 v41, v2
	v_mov_b32_e32 v50, v2
	v_mov_b32_e32 v51, v2
	v_mov_b32_e32 v52, v2
	v_mov_b32_e32 v53, v2
	v_mov_b32_e32 v54, v2
	v_mov_b32_e32 v55, v2
	v_mov_b32_e32 v56, v2
	v_mov_b32_e32 v57, v2
	v_mov_b32_e32 v10, v2
	v_mov_b32_e32 v11, v2
	v_mov_b32_e32 v12, v2
	v_mov_b32_e32 v13, v2
	v_mov_b32_e32 v14, v2
	v_mov_b32_e32 v15, v2
	v_mov_b32_e32 v16, v2
	v_mov_b32_e32 v17, v2
	v_mov_b32_e32 v26, v2
	v_mov_b32_e32 v27, v2
	v_mov_b32_e32 v28, v2
	v_mov_b32_e32 v29, v2
	v_mov_b32_e32 v30, v2
	v_mov_b32_e32 v31, v2
	v_mov_b32_e32 v32, v2
	v_mov_b32_e32 v33, v2
	v_mov_b32_e32 v42, v2
	v_mov_b32_e32 v43, v2
	v_mov_b32_e32 v44, v2
	v_mov_b32_e32 v45, v2
	v_mov_b32_e32 v46, v2
	v_mov_b32_e32 v47, v2
	v_mov_b32_e32 v48, v2
	v_mov_b32_e32 v49, v2
	v_mov_b32_e32 v58, v2
	v_mov_b32_e32 v59, v2
	v_mov_b32_e32 v60, v2
	v_mov_b32_e32 v61, v2
	v_mov_b32_e32 v62, v2
	v_mov_b32_e32 v63, v2
	v_mov_b32_e32 v64, v2
	v_mov_b32_e32 v65, v2
	v_mov_b32_e32 v66, v2
	v_mov_b32_e32 v67, v2
	v_mov_b32_e32 v68, v2
	v_mov_b32_e32 v69, v2
	v_mov_b32_e32 v70, v2
	v_mov_b32_e32 v71, v2
	v_mov_b32_e32 v72, v2
	v_mov_b32_e32 v73, v2
	v_mov_b32_e32 v82, v2
	v_mov_b32_e32 v83, v2
	v_mov_b32_e32 v84, v2
	v_mov_b32_e32 v85, v2
	v_mov_b32_e32 v86, v2
	v_mov_b32_e32 v87, v2
	v_mov_b32_e32 v88, v2
	v_mov_b32_e32 v89, v2
	v_mov_b32_e32 v98, v2
	v_mov_b32_e32 v99, v2
	v_mov_b32_e32 v100, v2
	v_mov_b32_e32 v101, v2
	v_mov_b32_e32 v102, v2
	v_mov_b32_e32 v103, v2
	v_mov_b32_e32 v104, v2
	v_mov_b32_e32 v105, v2
	v_mov_b32_e32 v114, v2
	v_mov_b32_e32 v115, v2
	v_mov_b32_e32 v116, v2
	v_mov_b32_e32 v117, v2
	v_mov_b32_e32 v118, v2
	v_mov_b32_e32 v119, v2
	v_mov_b32_e32 v120, v2
	v_mov_b32_e32 v121, v2
	v_mov_b32_e32 v74, v2
	v_mov_b32_e32 v75, v2
	v_mov_b32_e32 v76, v2
	v_mov_b32_e32 v77, v2
	v_mov_b32_e32 v78, v2
	v_mov_b32_e32 v79, v2
	v_mov_b32_e32 v80, v2
	v_mov_b32_e32 v81, v2
	v_mov_b32_e32 v90, v2
	v_mov_b32_e32 v91, v2
	v_mov_b32_e32 v92, v2
	v_mov_b32_e32 v93, v2
	v_mov_b32_e32 v94, v2
	v_mov_b32_e32 v95, v2
	v_mov_b32_e32 v96, v2
	v_mov_b32_e32 v97, v2
	v_mov_b32_e32 v106, v2
	v_mov_b32_e32 v107, v2
	v_mov_b32_e32 v108, v2
	v_mov_b32_e32 v109, v2
	v_mov_b32_e32 v110, v2
	v_mov_b32_e32 v111, v2
	v_mov_b32_e32 v112, v2
	v_mov_b32_e32 v113, v2
	v_mov_b32_e32 v122, v2
	v_mov_b32_e32 v123, v2
	v_mov_b32_e32 v124, v2
	v_mov_b32_e32 v125, v2
	v_mov_b32_e32 v126, v2
	v_mov_b32_e32 v127, v2
	v_mov_b32_e32 v128, v2
	v_mov_b32_e32 v129, v2
	v_readfirstlane_b32 s100, v130
	v_readfirstlane_b32 s101, v131
	s_nop 1
	s_sub_u32 s100, s100, 0x10000000
	s_subb_u32 s101, s101, 0
	v_add_u32_e32 v216, 0x10000, v144
	v_add_u32_e32 v217, 0x14000, v144
	v_add_u32_e32 v218, 0x18000, v144
	v_add_u32_e32 v219, 0x1c000, v144
.LBB0_862:
	s_add_i32 s47, s10, 0xfff00080
	s_cmp_eq_u32 s18, 60
	s_cselect_b32 s83, s45, s47
	s_cselect_b32 s82, s46, s11
	s_add_i32 s84, 0, 0x10000
	s_waitcnt lgkmcnt(0)
	s_add_i32 s86, 0, 0x14000
	ds_read_b128 v[136:139], v216
	ds_read_b128 v[146:149], v216 offset:1024
	ds_read_b128 v[150:153], v216 offset:2048
	ds_read_b128 v[154:157], v216 offset:3072
	ds_read_b128 v[158:161], v217
	ds_read_b128 v[162:165], v217 offset:1024
	ds_read_b128 v[166:169], v217 offset:2048
	ds_read_b128 v[170:173], v217 offset:3072
	s_add_i32 s47, s83, 0x80
	s_mov_b32 s87, s10
	ds_read_b128 v[174:177], v145
	ds_read_b128 v[178:181], v145 offset:1024
	ds_read_b128 v[182:185], v145 offset:2048
	ds_read_b128 v[186:189], v145 offset:3072
	ds_read_b128 v[190:193], v145 offset:4096
	ds_read_b128 v[194:197], v145 offset:5120
	ds_read_b128 v[198:201], v145 offset:6144
	ds_read_b128 v[202:205], v145 offset:7168
	s_add_i32 m0, s22, 0xc000
	s_add_i32 vcc_lo, s87, 0x10000000
	s_add_u32 vcc_lo, s100, vcc_lo
	s_addc_u32 vcc_hi, s101, 0
	global_load_lds_dwordx4 v140, vcc
	s_add_i32 m0, s22, 0xe000
	s_nop 0
	global_load_lds_dwordx4 v142, vcc
	s_waitcnt vmcnt(8)
	s_waitcnt lgkmcnt(0)
	s_barrier
; #define PG8_STAGE(bufoff, gbase, voff) do { unsigned _g = (gbase); asm volatile("" : "+s"(_g));   _Pragma("unroll") for (int _i = 0; _i < 2; ++_i) \
;         __builtin_amdgcn_global_load_lds((const unsigned*)(wsb + (size_t)(unsigned)(_g + (voff)[_i])), (LAS unsigned*)(lds + (bufoff) + ldsw + _i * 8192), 16, 0, 0); } while (0)
; #define PG8_WAIT_V(n) asm volatile("s_waitcnt vmcnt(" #n ")" ::: "memory")
; #define PG8_WAIT_L(n) asm volatile("s_waitcnt lgkmcnt(" #n ")" ::: "memory")
; #define PG8_BAR __builtin_amdgcn_s_barrier()
; #define PG8_SCHED __builtin_amdgcn_sched_barrier(0)
;     ...
;             PG8_WAIT_V(8); PG8_WAIT_L(0); PG8_BAR; PG8_MMA(0, 0, At, B0); PG8_MMA(0, 1, At, B1); PG8_BAR; PG8_SCHED;
;             PG8_LDA(At, 0, 1); PG8_STAGE(PG8_SB(0, 0), b2, voffB); PG8_STAGE(PG8_SB(0, 1), b2 + hstep, voffB); PG8_STAGE(PG8_SA(0, 0), a2, voffA);
;             PG8_WAIT_V(8); PG8_WAIT_L(0); PG8_BAR; PG8_MMA(1, 0, At, B0); PG8_MMA(1, 1, At, B1); PG8_BAR; PG8_SCHED;
;             PG8_LDB(B0, 1, 0); PG8_LDB(B1, 1, 1); PG8_SCHED; PG8_LDA(At, 1, 0); PG8_STAGE(PG8_SA(0, 1), a2 + hstep, voffA);
;             PG8_WAIT_V(8); PG8_WAIT_L(0); PG8_BAR; PG8_MMA(0, 0, At, B0); PG8_MMA(0, 1, At, B1); PG8_BAR; PG8_SCHED;
	s_setprio 1
	s_waitcnt lgkmcnt(0)
	v_mfma_f32_16x16x32_bf16 v[126:129], v[136:139], v[174:177], v[126:129]
	v_mfma_f32_16x16x32_bf16 v[122:125], v[150:153], v[174:177], v[122:125]
	v_mfma_f32_16x16x32_bf16 v[110:113], v[136:139], v[182:185], v[110:113]
	v_mfma_f32_16x16x32_bf16 v[106:109], v[150:153], v[182:185], v[106:109]
	v_mfma_f32_16x16x32_bf16 v[94:97], v[136:139], v[190:193], v[94:97]
	v_mfma_f32_16x16x32_bf16 v[90:93], v[150:153], v[190:193], v[90:93]
	v_mfma_f32_16x16x32_bf16 v[78:81], v[136:139], v[198:201], v[78:81]
	v_mfma_f32_16x16x32_bf16 v[74:77], v[150:153], v[198:201], v[74:77]
	v_mfma_f32_16x16x32_bf16 v[126:129], v[146:149], v[178:181], v[126:129]
	v_mfma_f32_16x16x32_bf16 v[122:125], v[154:157], v[178:181], v[122:125]
	v_mfma_f32_16x16x32_bf16 v[110:113], v[146:149], v[186:189], v[110:113]
	v_mfma_f32_16x16x32_bf16 v[106:109], v[154:157], v[186:189], v[106:109]
	v_mfma_f32_16x16x32_bf16 v[94:97], v[146:149], v[194:197], v[94:97]
	v_mfma_f32_16x16x32_bf16 v[90:93], v[154:157], v[194:197], v[90:93]
	v_mfma_f32_16x16x32_bf16 v[78:81], v[146:149], v[202:205], v[78:81]
	v_mfma_f32_16x16x32_bf16 v[74:77], v[154:157], v[202:205], v[74:77]
	s_setprio 0
	s_setprio 1
	v_mfma_f32_16x16x32_bf16 v[118:121], v[158:161], v[174:177], v[118:121]
	v_mfma_f32_16x16x32_bf16 v[114:117], v[166:169], v[174:177], v[114:117]
	v_mfma_f32_16x16x32_bf16 v[102:105], v[158:161], v[182:185], v[102:105]
	v_mfma_f32_16x16x32_bf16 v[98:101], v[166:169], v[182:185], v[98:101]
	v_mfma_f32_16x16x32_bf16 v[86:89], v[158:161], v[190:193], v[86:89]
	v_mfma_f32_16x16x32_bf16 v[82:85], v[166:169], v[190:193], v[82:85]
	v_mfma_f32_16x16x32_bf16 v[70:73], v[158:161], v[198:201], v[70:73]
	v_mfma_f32_16x16x32_bf16 v[66:69], v[166:169], v[198:201], v[66:69]
	v_mfma_f32_16x16x32_bf16 v[118:121], v[162:165], v[178:181], v[118:121]
	v_mfma_f32_16x16x32_bf16 v[114:117], v[170:173], v[178:181], v[114:117]
	v_mfma_f32_16x16x32_bf16 v[102:105], v[162:165], v[186:189], v[102:105]
	v_mfma_f32_16x16x32_bf16 v[98:101], v[170:173], v[186:189], v[98:101]
	v_mfma_f32_16x16x32_bf16 v[86:89], v[162:165], v[194:197], v[86:89]
	v_mfma_f32_16x16x32_bf16 v[82:85], v[170:173], v[194:197], v[82:85]
	v_mfma_f32_16x16x32_bf16 v[70:73], v[162:165], v[202:205], v[70:73]
	v_mfma_f32_16x16x32_bf16 v[66:69], v[170:173], v[202:205], v[66:69]
	s_setprio 0
	s_barrier
	s_mov_b32 s87, s82
	ds_read_b128 v[174:177], v145 offset:16384
	ds_read_b128 v[178:181], v145 offset:17408
	ds_read_b128 v[182:185], v145 offset:18432
	ds_read_b128 v[186:189], v145 offset:19456
	ds_read_b128 v[190:193], v145 offset:20480
	ds_read_b128 v[194:197], v145 offset:21504
	ds_read_b128 v[198:201], v145 offset:22528
	ds_read_b128 v[202:205], v145 offset:23552
	s_add_i32 s84, s84, s7
	s_add_i32 vcc_lo, s87, 0x10000000
	s_add_u32 vcc_lo, s100, vcc_lo
	s_addc_u32 vcc_hi, s101, 0
	s_mov_b32 m0, s84
	s_nop 0
	global_load_lds_dwordx4 v141, vcc
	s_add_i32 m0, s84, 0x2000
	s_add_i32 s84, s82, 0x100000
	global_load_lds_dwordx4 v143, vcc
	s_add_i32 s86, s86, s7
	s_add_i32 vcc_lo, s84, 0x10000000
	s_add_u32 vcc_lo, s100, vcc_lo
	s_addc_u32 vcc_hi, s101, 0
	s_mov_b32 m0, s86
	s_nop 0
	global_load_lds_dwordx4 v141, vcc
	s_add_i32 m0, s86, 0x2000
	s_mov_b32 s84, s83
	global_load_lds_dwordx4 v143, vcc
	s_mov_b32 m0, s22
	s_add_i32 vcc_lo, s84, 0x10000000
	s_add_u32 vcc_lo, s100, vcc_lo
	s_addc_u32 vcc_hi, s101, 0
	global_load_lds_dwordx4 v140, vcc
	s_mov_b32 m0, s23
	s_nop 0
	global_load_lds_dwordx4 v142, vcc
	s_waitcnt vmcnt(8)
	s_waitcnt lgkmcnt(0)
	s_barrier
	s_setprio 1
	s_waitcnt lgkmcnt(0)
	v_mfma_f32_16x16x32_bf16 v[62:65], v[136:139], v[174:177], v[62:65]
	v_mfma_f32_16x16x32_bf16 v[58:61], v[150:153], v[174:177], v[58:61]
	v_mfma_f32_16x16x32_bf16 v[46:49], v[136:139], v[182:185], v[46:49]
	v_mfma_f32_16x16x32_bf16 v[42:45], v[150:153], v[182:185], v[42:45]
	v_mfma_f32_16x16x32_bf16 v[30:33], v[136:139], v[190:193], v[30:33]
	v_mfma_f32_16x16x32_bf16 v[26:29], v[150:153], v[190:193], v[26:29]
	v_mfma_f32_16x16x32_bf16 v[14:17], v[136:139], v[198:201], v[14:17]
	v_mfma_f32_16x16x32_bf16 v[10:13], v[150:153], v[198:201], v[10:13]
	v_mfma_f32_16x16x32_bf16 v[62:65], v[146:149], v[178:181], v[62:65]
	v_mfma_f32_16x16x32_bf16 v[58:61], v[154:157], v[178:181], v[58:61]
	v_mfma_f32_16x16x32_bf16 v[46:49], v[146:149], v[186:189], v[46:49]
	v_mfma_f32_16x16x32_bf16 v[42:45], v[154:157], v[186:189], v[42:45]
	v_mfma_f32_16x16x32_bf16 v[30:33], v[146:149], v[194:197], v[30:33]
	v_mfma_f32_16x16x32_bf16 v[26:29], v[154:157], v[194:197], v[26:29]
	v_mfma_f32_16x16x32_bf16 v[14:17], v[146:149], v[202:205], v[14:17]
	v_mfma_f32_16x16x32_bf16 v[10:13], v[154:157], v[202:205], v[10:13]
	s_setprio 0
	s_setprio 1
	v_mfma_f32_16x16x32_bf16 v[54:57], v[158:161], v[174:177], v[54:57]
	v_mfma_f32_16x16x32_bf16 v[50:53], v[166:169], v[174:177], v[50:53]
	v_mfma_f32_16x16x32_bf16 v[38:41], v[158:161], v[182:185], v[38:41]
	v_mfma_f32_16x16x32_bf16 v[34:37], v[166:169], v[182:185], v[34:37]
	v_mfma_f32_16x16x32_bf16 v[22:25], v[158:161], v[190:193], v[22:25]
	v_mfma_f32_16x16x32_bf16 v[18:21], v[166:169], v[190:193], v[18:21]
	v_mfma_f32_16x16x32_bf16 v[6:9], v[158:161], v[198:201], v[6:9]
	v_mfma_f32_16x16x32_bf16 v[2:5], v[166:169], v[198:201], v[2:5]
	v_mfma_f32_16x16x32_bf16 v[54:57], v[162:165], v[178:181], v[54:57]
	v_mfma_f32_16x16x32_bf16 v[50:53], v[170:173], v[178:181], v[50:53]
	v_mfma_f32_16x16x32_bf16 v[38:41], v[162:165], v[186:189], v[38:41]
	v_mfma_f32_16x16x32_bf16 v[34:37], v[170:173], v[186:189], v[34:37]
	v_mfma_f32_16x16x32_bf16 v[22:25], v[162:165], v[194:197], v[22:25]
	v_mfma_f32_16x16x32_bf16 v[18:21], v[170:173], v[194:197], v[18:21]
	v_mfma_f32_16x16x32_bf16 v[6:9], v[162:165], v[202:205], v[6:9]
	v_mfma_f32_16x16x32_bf16 v[2:5], v[170:173], v[202:205], v[2:5]
	s_setprio 0
	s_barrier
; #define PG8_STAGE(bufoff, gbase, voff) do { unsigned _g = (gbase); asm volatile("" : "+s"(_g));   _Pragma("unroll") for (int _i = 0; _i < 2; ++_i) \
;         __builtin_amdgcn_global_load_lds((const unsigned*)(wsb + (size_t)(unsigned)(_g + (voff)[_i])), (LAS unsigned*)(lds + (bufoff) + ldsw + _i * 8192), 16, 0, 0); } while (0)
; #define PG8_WAIT_V(n) asm volatile("s_waitcnt vmcnt(" #n ")" ::: "memory")
; #define PG8_WAIT_L(n) asm volatile("s_waitcnt lgkmcnt(" #n ")" ::: "memory")
; #define PG8_BAR __builtin_amdgcn_s_barrier()
; #define PG8_SCHED __builtin_amdgcn_sched_barrier(0)
;     ...
;             PG8_LDB(B0, 1, 0); PG8_LDB(B1, 1, 1); PG8_SCHED; PG8_LDA(At, 1, 0); PG8_STAGE(PG8_SA(0, 1), a2 + hstep, voffA);
;             PG8_WAIT_V(8); PG8_WAIT_L(0); PG8_BAR; PG8_MMA(0, 0, At, B0); PG8_MMA(0, 1, At, B1); PG8_BAR; PG8_SCHED;
;             PG8_LDA(At, 1, 1); PG8_STAGE(PG8_SB(1, 0), b3, voffB); PG8_STAGE(PG8_SB(1, 1), b3 + hstep, voffB); PG8_STAGE(PG8_SA(1, 0), a3, voffA);
;             PG8_WAIT_V(8); PG8_WAIT_L(0); PG8_BAR; PG8_MMA(1, 0, At, B0); PG8_MMA(1, 1, At, B1); PG8_BAR; PG8_SCHED;
	s_add_i32 s84, 0, 0x18000
	s_add_i32 s86, 0, 0x1c000
	ds_read_b128 v[136:139], v218
	ds_read_b128 v[146:149], v218 offset:1024
	ds_read_b128 v[150:153], v218 offset:2048
	ds_read_b128 v[154:157], v218 offset:3072
	ds_read_b128 v[158:161], v219
	ds_read_b128 v[162:165], v219 offset:1024
	ds_read_b128 v[166:169], v219 offset:2048
	ds_read_b128 v[170:173], v219 offset:3072
	s_add_i32 s83, s83, 0x100000
	ds_read_b128 v[174:177], v145 offset:32768
	ds_read_b128 v[178:181], v145 offset:33792
	ds_read_b128 v[182:185], v145 offset:34816
	ds_read_b128 v[186:189], v145 offset:35840
	ds_read_b128 v[190:193], v145 offset:36864
	ds_read_b128 v[194:197], v145 offset:37888
	ds_read_b128 v[198:201], v145 offset:38912
	ds_read_b128 v[202:205], v145 offset:39936
	s_mov_b32 m0, s24
	s_add_i32 vcc_lo, s83, 0x10000000
	s_add_u32 vcc_lo, s100, vcc_lo
	s_addc_u32 vcc_hi, s101, 0
	global_load_lds_dwordx4 v140, vcc
	s_mov_b32 m0, s25
	s_nop 0
	global_load_lds_dwordx4 v142, vcc
	s_waitcnt vmcnt(8)
	s_waitcnt lgkmcnt(0)
	s_barrier
	s_setprio 1
	s_waitcnt lgkmcnt(0)
	v_mfma_f32_16x16x32_bf16 v[126:129], v[136:139], v[174:177], v[126:129]
	v_mfma_f32_16x16x32_bf16 v[122:125], v[150:153], v[174:177], v[122:125]
	v_mfma_f32_16x16x32_bf16 v[110:113], v[136:139], v[182:185], v[110:113]
	v_mfma_f32_16x16x32_bf16 v[106:109], v[150:153], v[182:185], v[106:109]
	v_mfma_f32_16x16x32_bf16 v[94:97], v[136:139], v[190:193], v[94:97]
	v_mfma_f32_16x16x32_bf16 v[90:93], v[150:153], v[190:193], v[90:93]
	v_mfma_f32_16x16x32_bf16 v[78:81], v[136:139], v[198:201], v[78:81]
	v_mfma_f32_16x16x32_bf16 v[74:77], v[150:153], v[198:201], v[74:77]
	v_mfma_f32_16x16x32_bf16 v[126:129], v[146:149], v[178:181], v[126:129]
	v_mfma_f32_16x16x32_bf16 v[122:125], v[154:157], v[178:181], v[122:125]
	v_mfma_f32_16x16x32_bf16 v[110:113], v[146:149], v[186:189], v[110:113]
	v_mfma_f32_16x16x32_bf16 v[106:109], v[154:157], v[186:189], v[106:109]
	v_mfma_f32_16x16x32_bf16 v[94:97], v[146:149], v[194:197], v[94:97]
	v_mfma_f32_16x16x32_bf16 v[90:93], v[154:157], v[194:197], v[90:93]
	v_mfma_f32_16x16x32_bf16 v[78:81], v[146:149], v[202:205], v[78:81]
	v_mfma_f32_16x16x32_bf16 v[74:77], v[154:157], v[202:205], v[74:77]
	s_setprio 0
	s_setprio 1
	v_mfma_f32_16x16x32_bf16 v[118:121], v[158:161], v[174:177], v[118:121]
	v_mfma_f32_16x16x32_bf16 v[114:117], v[166:169], v[174:177], v[114:117]
	v_mfma_f32_16x16x32_bf16 v[102:105], v[158:161], v[182:185], v[102:105]
	v_mfma_f32_16x16x32_bf16 v[98:101], v[166:169], v[182:185], v[98:101]
	v_mfma_f32_16x16x32_bf16 v[86:89], v[158:161], v[190:193], v[86:89]
	v_mfma_f32_16x16x32_bf16 v[82:85], v[166:169], v[190:193], v[82:85]
	v_mfma_f32_16x16x32_bf16 v[70:73], v[158:161], v[198:201], v[70:73]
	v_mfma_f32_16x16x32_bf16 v[66:69], v[166:169], v[198:201], v[66:69]
	v_mfma_f32_16x16x32_bf16 v[118:121], v[162:165], v[178:181], v[118:121]
	v_mfma_f32_16x16x32_bf16 v[114:117], v[170:173], v[178:181], v[114:117]
	v_mfma_f32_16x16x32_bf16 v[102:105], v[162:165], v[186:189], v[102:105]
	v_mfma_f32_16x16x32_bf16 v[98:101], v[170:173], v[186:189], v[98:101]
	v_mfma_f32_16x16x32_bf16 v[86:89], v[162:165], v[194:197], v[86:89]
	v_mfma_f32_16x16x32_bf16 v[82:85], v[170:173], v[194:197], v[82:85]
	v_mfma_f32_16x16x32_bf16 v[70:73], v[162:165], v[202:205], v[70:73]
	v_mfma_f32_16x16x32_bf16 v[66:69], v[170:173], v[202:205], v[66:69]
	s_setprio 0
	s_barrier
	s_add_i32 s83, s82, 0x80
	ds_read_b128 v[174:177], v145 offset:49152
	ds_read_b128 v[178:181], v145 offset:50176
	ds_read_b128 v[182:185], v145 offset:51200
	ds_read_b128 v[186:189], v145 offset:52224
	ds_read_b128 v[190:193], v145 offset:53248
	ds_read_b128 v[194:197], v145 offset:54272
	ds_read_b128 v[198:201], v145 offset:55296
	ds_read_b128 v[202:205], v145 offset:56320
	s_add_i32 s84, s84, s7
	s_add_i32 vcc_lo, s83, 0x10000000
	s_add_u32 vcc_lo, s100, vcc_lo
	s_addc_u32 vcc_hi, s101, 0
	s_mov_b32 m0, s84
	s_nop 0
	global_load_lds_dwordx4 v141, vcc
	s_add_i32 m0, s84, 0x2000
	s_add_i32 s82, s82, 0x100080
	global_load_lds_dwordx4 v143, vcc
	s_add_i32 s83, s86, s7
	s_add_i32 vcc_lo, s82, 0x10000000
	s_add_u32 vcc_lo, s100, vcc_lo
	s_addc_u32 vcc_hi, s101, 0
	s_mov_b32 m0, s83
	s_nop 0
	global_load_lds_dwordx4 v141, vcc
	s_add_i32 m0, s83, 0x2000
	s_nop 0
	global_load_lds_dwordx4 v143, vcc
	s_mov_b32 m0, s36
	s_add_i32 vcc_lo, s47, 0x10000000
	s_add_u32 vcc_lo, s100, vcc_lo
	s_addc_u32 vcc_hi, s101, 0
	global_load_lds_dwordx4 v140, vcc
	s_mov_b32 m0, s37
	s_nop 0
	global_load_lds_dwordx4 v142, vcc
	s_waitcnt vmcnt(8)
	s_waitcnt lgkmcnt(0)
	s_barrier
; #define GAS __attribute__((address_space(1)))
; __device__ __forceinline__ unsigned cvt_pk_bf16(float lo, float hi) { const f32x2_t_ v = {lo, hi}; const bf16x2_t_ b = __builtin_convertvector(v, bf16x2_t_); return __builtin_bit_cast(unsigned, b); }
; #define PG8_STAGE(bufoff, gbase, voff) do { unsigned _g = (gbase); asm volatile("" : "+s"(_g));   _Pragma("unroll") for (int _i = 0; _i < 2; ++_i) \
;         __builtin_amdgcn_global_load_lds((const unsigned*)(wsb + (size_t)(unsigned)(_g + (voff)[_i])), (LAS unsigned*)(lds + (bufoff) + ldsw + _i * 8192), 16, 0, 0); } while (0)
; #define PG8_WAIT_V(n) asm volatile("s_waitcnt vmcnt(" #n ")" ::: "memory")
; #define PG8_WAIT_L(n) asm volatile("s_waitcnt lgkmcnt(" #n ")" ::: "memory")
;     ...
;             PG8_WAIT_V(8); PG8_WAIT_L(0); PG8_BAR; PG8_MMA(0, 0, At, B0); PG8_MMA(0, 1, At, B1); PG8_BAR; PG8_SCHED;
;             PG8_LDA(At, 1, 1); PG8_STAGE(PG8_SB(1, 0), b3, voffB); PG8_STAGE(PG8_SB(1, 1), b3 + hstep, voffB); PG8_STAGE(PG8_SA(1, 0), a3, voffA);
;             PG8_WAIT_V(8); PG8_WAIT_L(0); PG8_BAR; PG8_MMA(1, 0, At, B0); PG8_MMA(1, 1, At, B1); PG8_BAR; PG8_SCHED;
;     __device__ __forceinline__ void operator()(const f32x4 (&acc)[2][2][4][2], const pg8::GUnit& u, int wr, int wc, int fr, int fq) const {
;         const int row0 = u.pm * 256 + wr * 64 + fr, col0 = u.pn * 256 + wc * 32 + 8 * fq;
; #pragma unroll
;         for (int ai = 0; ai < 2; ++ai)
; #pragma unroll
;             for (int m = 0; m < 4; ++m) { const size_t row = (size_t)(row0 + ai * 128 + m * 16); float s = 0.f;
; #pragma unroll
;                 for (int bj = 0; bj < 2; ++bj) { const f32x4 v0 = acc[ai][bj][m][0], v1 = acc[ai][bj][m][1];
;                     s += (v0[0] * v0[0] + v0[1] * v0[1]) + (v0[2] * v0[2] + v0[3] * v0[3]) + (v1[0] * v1[0] + v1[1] * v1[1]) + (v1[2] * v1[2] + v1[3] * v1[3]);
;                     u32x4 w; w.x = cvt_pk_bf16(v0[0], v0[1]); w.y = cvt_pk_bf16(v0[2], v0[3]); w.z = cvt_pk_bf16(v1[0], v1[1]); w.w = cvt_pk_bf16(v1[2], v1[3]);
;                     *(GAS u32x4*)((GAS bf16_t*)O + row * DM + col0 + bj * 128) = w; }
;                 { const int ln = fr + 16 * fq; s += __int_as_float(__builtin_amdgcn_ds_bpermute((ln ^ 16) << 2, __float_as_int(s))); s += __int_as_float(__builtin_amdgcn_ds_bpermute((ln ^ 32) << 2, __float_as_int(s))); }
;                 if (fq == 0) ((GAS float*)RSQ)[row * 64 + u.pn * 4 + wc] = s; }
	s_setprio 1
	s_waitcnt lgkmcnt(0)
	v_mfma_f32_16x16x32_bf16 v[62:65], v[136:139], v[174:177], v[62:65]
	v_mfma_f32_16x16x32_bf16 v[58:61], v[150:153], v[174:177], v[58:61]
	v_mfma_f32_16x16x32_bf16 v[46:49], v[136:139], v[182:185], v[46:49]
	v_mfma_f32_16x16x32_bf16 v[42:45], v[150:153], v[182:185], v[42:45]
	v_mfma_f32_16x16x32_bf16 v[30:33], v[136:139], v[190:193], v[30:33]
	v_mfma_f32_16x16x32_bf16 v[26:29], v[150:153], v[190:193], v[26:29]
	v_mfma_f32_16x16x32_bf16 v[14:17], v[136:139], v[198:201], v[14:17]
	v_mfma_f32_16x16x32_bf16 v[10:13], v[150:153], v[198:201], v[10:13]
	v_mfma_f32_16x16x32_bf16 v[62:65], v[146:149], v[178:181], v[62:65]
	v_mfma_f32_16x16x32_bf16 v[58:61], v[154:157], v[178:181], v[58:61]
	v_mfma_f32_16x16x32_bf16 v[46:49], v[146:149], v[186:189], v[46:49]
	v_mfma_f32_16x16x32_bf16 v[42:45], v[154:157], v[186:189], v[42:45]
	v_mfma_f32_16x16x32_bf16 v[30:33], v[146:149], v[194:197], v[30:33]
	v_mfma_f32_16x16x32_bf16 v[26:29], v[154:157], v[194:197], v[26:29]
	v_mfma_f32_16x16x32_bf16 v[14:17], v[146:149], v[202:205], v[14:17]
	v_mfma_f32_16x16x32_bf16 v[10:13], v[154:157], v[202:205], v[10:13]
	s_setprio 0
	s_setprio 1
	v_mfma_f32_16x16x32_bf16 v[54:57], v[158:161], v[174:177], v[54:57]
	v_mfma_f32_16x16x32_bf16 v[50:53], v[166:169], v[174:177], v[50:53]
	v_mfma_f32_16x16x32_bf16 v[38:41], v[158:161], v[182:185], v[38:41]
	v_mfma_f32_16x16x32_bf16 v[34:37], v[166:169], v[182:185], v[34:37]
	v_mfma_f32_16x16x32_bf16 v[22:25], v[158:161], v[190:193], v[22:25]
	v_mfma_f32_16x16x32_bf16 v[18:21], v[166:169], v[190:193], v[18:21]
	v_mfma_f32_16x16x32_bf16 v[6:9], v[158:161], v[198:201], v[6:9]
	v_mfma_f32_16x16x32_bf16 v[2:5], v[166:169], v[198:201], v[2:5]
	v_mfma_f32_16x16x32_bf16 v[54:57], v[162:165], v[178:181], v[54:57]
	v_mfma_f32_16x16x32_bf16 v[50:53], v[170:173], v[178:181], v[50:53]
	v_mfma_f32_16x16x32_bf16 v[38:41], v[162:165], v[186:189], v[38:41]
	v_mfma_f32_16x16x32_bf16 v[34:37], v[170:173], v[186:189], v[34:37]
	v_mfma_f32_16x16x32_bf16 v[22:25], v[162:165], v[194:197], v[22:25]
	v_mfma_f32_16x16x32_bf16 v[18:21], v[170:173], v[194:197], v[18:21]
	v_mfma_f32_16x16x32_bf16 v[6:9], v[162:165], v[202:205], v[6:9]
	v_mfma_f32_16x16x32_bf16 v[2:5], v[170:173], v[202:205], v[2:5]
	s_setprio 0
	s_barrier
	s_add_i32 s18, s18, 2
	s_addk_i32 s10, 0x100
	s_addk_i32 s11, 0x100
	s_cmp_gt_u32 s18, 61
	s_cbranch_scc0 .LBB0_862
	s_lshl_b32 s9, s9, 8
	v_mbcnt_lo_u32_b32 v139, -1, 0
	v_mbcnt_hi_u32_b32 v139, -1, v139
	s_add_i32 s9, s9, s3
	v_and_b32_e32 v0, 15, v139
	v_ashrrev_i32_e32 v146, 4, v139
	v_or_b32_e32 v138, s9, v0
	s_lshl_b32 s9, s8, 8
	s_or_b32 s9, s9, s88
	v_lshlrev_b32_e32 v147, 6, v146
	v_lshlrev_b32_e32 v0, 2, v0
	v_lshl_add_u32 v136, v146, 3, s9
	v_bitop3_b32 v146, v147, 64, v0 bitop3:0x36
	v_bitop3_b32 v0, v147, s92, v0 bitop3:0x36
	v_mul_f32_e32 v147, v127, v127
	v_mul_f32_e32 v150, v129, v129
	v_fmac_f32_e32 v147, v126, v126
	v_fmac_f32_e32 v150, v128, v128
	v_add_f32_e32 v147, v147, v150
	v_mul_f32_e32 v150, v123, v123
	v_fmac_f32_e32 v150, v122, v122
	v_cvt_pk_bf16_f32 v126, v126, v127
	v_cvt_pk_bf16_f32 v127, v128, v129
	v_cvt_pk_bf16_f32 v128, v122, v123
	v_mul_f32_e32 v122, v119, v119
	v_mul_f32_e32 v123, v121, v121
	v_fmac_f32_e32 v122, v118, v118
	v_fmac_f32_e32 v123, v120, v120
	v_add_f32_e32 v122, v122, v123
	v_mul_f32_e32 v123, v115, v115
	v_fmac_f32_e32 v123, v114, v114
	v_add_f32_e32 v147, v147, v150
	v_mul_f32_e32 v150, v125, v125
	v_add_f32_e32 v122, v122, v123
	v_mul_f32_e32 v123, v117, v117
	v_fmac_f32_e32 v150, v124, v124
	v_fmac_f32_e32 v123, v116, v116
	v_add_f32_e32 v147, v150, v147
	v_add_f32_e32 v122, v123, v122
	v_cvt_pk_bf16_f32 v129, v124, v125
	v_add_f32_e32 v124, v147, v122
	ds_bpermute_b32 v125, v146, v124
	v_cmp_gt_u32_e32 vcc, 16, v139
	v_ashrrev_i32_e32 v139, 31, v138
	v_lshlrev_b64 v[148:149], 13, v[138:139]
	v_ashrrev_i32_e32 v137, 31, v136
	v_lshl_add_u64 v[122:123], v[132:133], 0, v[148:149]
	v_lshl_add_u64 v[148:149], v[136:137], 1, v[122:123]
	v_cvt_pk_bf16_f32 v122, v118, v119
	s_waitcnt lgkmcnt(0)
	v_add_f32_e32 v118, v124, v125
	ds_bpermute_b32 v119, v0, v118
	s_lshl_b32 s8, s8, 2
	s_ashr_i32 s9, s8, 31
	v_cvt_pk_bf16_f32 v123, v120, v121
	v_cvt_pk_bf16_f32 v124, v114, v115
	v_cvt_pk_bf16_f32 v125, v116, v117
	global_store_dwordx4 v[148:149], v[126:129], off
	global_store_dwordx4 v[148:149], v[122:125], off offset:256
	s_and_saveexec_b64 s[10:11], vcc
	s_cbranch_execz .LBB0_865
	v_lshlrev_b64 v[114:115], 8, v[138:139]
	v_lshl_add_u64 v[114:115], v[134:135], 0, v[114:115]
	v_lshl_add_u64 v[114:115], s[8:9], 2, v[114:115]
	s_lshl_b32 s18, s43, 2
	s_waitcnt lgkmcnt(0)
	v_add_f32_e32 v116, v118, v119
	v_lshl_add_u64 v[114:115], v[114:115], 0, s[18:19]
	global_store_dword v[114:115], v116, off
